# v28 + one static s_setprio 1 for waves 4-7 at kernel entry (priority raise for one wave half through all MFMA mainloops)
# baseline (speedup 1.0000x reference)
_Z14fwd_megakernel6Params:
	s_load_dwordx8 s[88:95], s[0:1], 0x180
	s_mov_b32 s96, s2
	v_readfirstlane_b32 s98, v0
	s_nop 3
	s_and_b32 s98, s98, 0x3ff
	s_lshr_b32 s98, s98, 6
	s_cmp_ge_u32 s98, 4
	s_cbranch_scc0 .Lprio_done
	s_setprio 1
.Lprio_done:
	v_cmp_eq_u32_e64 s[4:5], 0, v0
	s_mov_b64 s[2:3], exec
	s_nop 0
	v_writelane_b32 v197, s4, 0
	s_nop 1
	v_writelane_b32 v197, s5, 1
	s_and_b64 s[4:5], s[2:3], s[4:5]
	s_mov_b64 exec, s[4:5]
	s_cbranch_execz .LBB0_2
	s_add_i32 s4, 0, 0x24010
	v_mov_b32_e32 v1, 0
	v_mov_b32_e32 v2, s4
	s_add_i32 s4, 0, 0x24014
	ds_write_b32 v2, v1
	v_mov_b32_e32 v2, s4
	ds_write_b32 v2, v1
